# attention main loop: forgetting bias added by v_mfma_f32_32x32x2_f32 (f32 operands) into the QK accumulate chain instead of 64 v_add_f32 + 16 bias ds_read_b128 per step pair
# baseline (speedup 1.0000x reference)
.LBB0_1314:
	v_lshlrev_b32_e32 v0, 1, v216
	v_and_b32_e32 v223, 32, v0
	v_lshrrev_b32_e32 v0, 2, v216
	v_and_or_b32 v0, v0, 3, v221
	v_lshlrev_b32_e32 v222, 6, v0
	v_add_u32_e32 v0, 0, v223
	v_add3_u32 v240, v0, v220, v222
	v_max3_f32 v0, v2, v3, v18
	v_max3_f32 v34, v4, v5, v19
	s_lshl_b32 s71, s24, 8
	v_max3_f32 v0, v0, v20, v21
	v_max3_f32 v34, v34, v8, v9
	s_and_b32 s17, s17, 0x3fffffc0
	v_max3_f32 v0, v0, v6, v7
	v_max3_f32 v34, v34, v24, v25
	s_add_i32 s76, s71, 0x100
	v_max3_f32 v0, v0, v22, v23
	v_max3_f32 v34, v34, v12, v13
	s_lshl_b32 s17, s17, 2
	v_max3_f32 v0, v0, v10, v11
	v_max3_f32 v34, v34, v28, v29
	s_add_i32 s17, s17, 0
	v_max3_f32 v0, v0, v26, v27
	v_max3_f32 v34, v34, v16, v17
	s_lshr_b32 s77, s76, 6
	v_max3_f32 v0, v0, v14, v15
	v_max3_f32 v34, v34, v32, v33
	s_mov_b64 s[22:23], 0x30000
	v_max3_f32 v0, v0, v30, v31
	s_cmp_lg_u32 0, -1
	v_max_f32_e32 v0, v0, v34
	s_mov_b32 s50, 1
	v_mov_b32_e32 v34, v0
	s_nop 1
	v_permlane32_swap_b32_e32 v0, v34
	v_max_f32_e32 v0, v0, v34
	s_mov_b32 s25, 0
	v_add_f32_e32 v229, v1, v0
	v_sub_f32_e32 v2, v2, v0
	v_sub_f32_e32 v3, v3, v0
	v_sub_f32_e32 v18, v18, v0
	v_sub_f32_e32 v19, v19, v0
	v_sub_f32_e32 v4, v4, v0
	s_nop 0
	v_xor_b32_e32 v48, 0x80000000, v229
	v_mov_b32_e32 v49, v48
	v_mov_b32_e32 v50, v48
	v_mov_b32_e32 v51, v48
	v_mov_b32_e32 v52, v48
	v_mov_b32_e32 v53, v48
	v_mov_b32_e32 v54, v48
	v_mov_b32_e32 v55, v48
	v_mov_b32_e32 v56, v48
	v_mov_b32_e32 v57, v48
	v_mov_b32_e32 v58, v48
	v_mov_b32_e32 v59, v48
	v_mov_b32_e32 v60, v48
	v_mov_b32_e32 v61, v48
	v_mov_b32_e32 v62, v48
	v_mov_b32_e32 v63, v48
	s_waitcnt vmcnt(0) lgkmcnt(0)
	s_barrier
	v_exp_f32_e32 v80, v2
	v_exp_f32_e32 v81, v3
	v_lshl_add_u64 v[2:3], v[212:213], 0, s[22:23]
	s_mov_b32 s22, m0
	s_mov_b32 m0, s74
	s_nop 0
	global_load_lds_dwordx4 v[2:3], off
	s_mov_b32 m0, s22
	s_cselect_b32 s22, 0, 0
	s_add_i32 s16, s22, s16
	v_lshl_add_u64 v[2:3], v[214:215], 0, s[30:31]
	s_add_i32 s16, s16, 0x8000
	s_mov_b32 s22, m0
	s_mov_b32 m0, s16
	s_nop 0
	global_load_lds_dwordx4 v[2:3], off
	s_mov_b32 m0, s22
	ds_read_b128 v[188:191], v228 offset:8192
	ds_read_b128 v[184:187], v228 offset:8704
	ds_read_b128 v[180:183], v228 offset:10240
	ds_read_b128 v[176:179], v228 offset:10752
	ds_read_b128 v[172:175], v228 offset:12288
	ds_read_b128 v[168:171], v228 offset:12800
	ds_read_b128 v[164:167], v228 offset:14336
	ds_read_b128 v[160:163], v228 offset:14848
	v_sub_f32_e32 v20, v20, v0
	v_sub_f32_e32 v5, v5, v0
	v_sub_f32_e32 v21, v21, v0
	v_sub_f32_e32 v6, v6, v0
	v_sub_f32_e32 v22, v22, v0
	v_sub_f32_e32 v7, v7, v0
	v_sub_f32_e32 v23, v23, v0
	v_sub_f32_e32 v8, v8, v0
	v_sub_f32_e32 v24, v24, v0
	v_sub_f32_e32 v9, v9, v0
	v_sub_f32_e32 v25, v25, v0
	v_sub_f32_e32 v10, v10, v0
	v_sub_f32_e32 v26, v26, v0
	v_sub_f32_e32 v11, v11, v0
	v_sub_f32_e32 v27, v27, v0
	v_sub_f32_e32 v12, v12, v0
	v_sub_f32_e32 v28, v28, v0
	v_sub_f32_e32 v13, v13, v0
	v_sub_f32_e32 v29, v29, v0
	v_sub_f32_e32 v14, v14, v0
	v_sub_f32_e32 v30, v30, v0
	v_sub_f32_e32 v15, v15, v0
	v_sub_f32_e32 v31, v31, v0
	v_sub_f32_e32 v16, v16, v0
	v_sub_f32_e32 v32, v32, v0
	v_sub_f32_e32 v17, v17, v0
	v_sub_f32_e32 v0, v33, v0
	v_exp_f32_e32 v82, v4
	v_exp_f32_e32 v83, v5
	v_exp_f32_e32 v84, v6
	v_exp_f32_e32 v85, v7
	v_exp_f32_e32 v86, v8
	v_exp_f32_e32 v87, v9
	v_exp_f32_e32 v88, v10
	v_exp_f32_e32 v89, v11
	v_exp_f32_e32 v90, v12
	v_exp_f32_e32 v91, v13
	v_exp_f32_e32 v92, v14
	v_exp_f32_e32 v93, v15
	v_exp_f32_e32 v94, v16
	v_exp_f32_e32 v95, v17
	v_exp_f32_e32 v64, v18
	v_exp_f32_e32 v65, v19
	v_exp_f32_e32 v66, v20
	v_exp_f32_e32 v67, v21
	v_exp_f32_e32 v68, v22
	v_exp_f32_e32 v69, v23
	v_exp_f32_e32 v70, v24
	v_exp_f32_e32 v71, v25
	v_exp_f32_e32 v72, v26
	v_exp_f32_e32 v73, v27
	v_exp_f32_e32 v74, v28
	v_exp_f32_e32 v75, v29
	v_exp_f32_e32 v76, v30
	v_exp_f32_e32 v77, v31
	v_exp_f32_e32 v78, v32
	v_exp_f32_e32 v79, v0
	s_waitcnt vmcnt(2) lgkmcnt(0)
	s_barrier
	s_andn2_b64 vcc, exec, s[2:3]
	v_cmp_gt_u32_e64 s[2:3], 32, v217
	v_lshl_add_u32 v226, v218, 2, s17
	v_lshl_add_u32 v224, v221, 2, s17
	s_cbranch_vccnz .LBB0_1330
	v_mov_b32_e32 v14, v1
	v_mov_b32_e32 v15, v1
	v_readlane_b32 s16, v255, 9
	v_mov_b32_e32 v0, v1
	v_mov_b32_e32 v2, v1
	v_mov_b32_e32 v3, v1
	v_mov_b32_e32 v4, v1
	v_mov_b32_e32 v5, v1
	v_mov_b32_e32 v6, v1
	v_mov_b32_e32 v7, v1
	v_mov_b32_e32 v8, v1
	v_mov_b32_e32 v9, v1
	v_mov_b32_e32 v10, v1
	v_mov_b32_e32 v11, v1
	v_mov_b32_e32 v12, v1
	v_mov_b32_e32 v13, v1
	v_mov_b64_e32 v[46:47], v[14:15]
	v_mov_b64_e32 v[30:31], v[14:15]
	v_lshl_add_u32 v200, v219, 4, s16
	v_mbcnt_lo_u32_b32 v236, -1, 0
	v_mbcnt_hi_u32_b32 v236, -1, v236
	v_and_b32_e32 v237, 31, v236
	v_lshl_add_u32 v237, v237, 2, s16
	v_cmp_gt_u32_e64 s[100:101], 32, v236
	v_cndmask_b32_e64 v236, 0, 1.0, s[100:101]
	ds_read_b32 v230, v237
	ds_read_b32 v231, v237 offset:128
	s_waitcnt lgkmcnt(0)
	s_mov_b32 s16, 0
	s_movk_i32 s25, 0x4000
	s_movk_i32 s50, 0x2000
	v_mov_b32_e32 v241, 0
	s_mov_b32 s46, 6
	s_mov_b32 s47, 0x20000
	v_mov_b64_e32 v[44:45], v[12:13]
	v_mov_b64_e32 v[42:43], v[10:11]
	v_mov_b64_e32 v[40:41], v[8:9]
	v_mov_b64_e32 v[38:39], v[6:7]
	v_mov_b64_e32 v[36:37], v[4:5]
	v_mov_b64_e32 v[34:35], v[2:3]
	v_mov_b64_e32 v[32:33], v[0:1]
	v_mov_b64_e32 v[28:29], v[12:13]
	v_mov_b64_e32 v[26:27], v[10:11]
	v_mov_b64_e32 v[24:25], v[8:9]
	v_mov_b64_e32 v[22:23], v[6:7]
	v_mov_b64_e32 v[20:21], v[4:5]
	v_mov_b64_e32 v[18:19], v[2:3]
	v_mov_b64_e32 v[16:17], v[0:1]
	.p2align	6
.LBB0_1316:
	s_waitcnt lgkmcnt(8)
	v_mfma_f32_32x32x2_f32 v[96:111], v230, v236, v[48:63]
	v_add_u32_e32 v0, s16, v240
	ds_read_b64_tr_b16 v[192:193], v0 offset:24576
	ds_read_b64_tr_b16 v[194:195], v0 offset:25088
	v_add_f32_e32 v2, v80, v81
	v_add_f32_e32 v2, v82, v2
	v_add_f32_e32 v2, v83, v2
	v_add_f32_e32 v2, v84, v2
	v_add_f32_e32 v2, v85, v2
	v_cvt_pk_bf16_f32 v156, v80, v81
	v_cvt_pk_bf16_f32 v157, v82, v83
	s_waitcnt lgkmcnt(9)
	v_mfma_f32_32x32x16_bf16 v[96:111], v[188:191], v[140:143], v[96:111]
	ds_read_b64_tr_b16 v[188:189], v0 offset:28672
	ds_read_b64_tr_b16 v[190:191], v0 offset:29184
	v_add_f32_e32 v2, v86, v2
	v_add_f32_e32 v2, v87, v2
	v_add_f32_e32 v2, v88, v2
	v_add_f32_e32 v2, v89, v2
	v_cvt_pk_bf16_f32 v158, v84, v85
	v_cvt_pk_bf16_f32 v159, v86, v87
	s_waitcnt lgkmcnt(10)
	v_mfma_f32_32x32x2_f32 v[112:127], v231, v236, v[48:63]
	v_mfma_f32_32x32x16_bf16 v[112:127], v[184:187], v[140:143], v[112:127]
	ds_read_b64_tr_b16 v[10:11], v0 offset:25600
	ds_read_b64_tr_b16 v[12:13], v0 offset:26112
	v_add_f32_e32 v2, v90, v2
	v_add_f32_e32 v2, v91, v2
	v_add_f32_e32 v2, v92, v2
	v_add_f32_e32 v2, v93, v2
	v_cvt_pk_bf16_f32 v152, v88, v89
	v_cvt_pk_bf16_f32 v153, v90, v91
	s_waitcnt lgkmcnt(11)
	v_mfma_f32_32x32x16_bf16 v[96:111], v[180:183], v[136:139], v[96:111]
	ds_read_b64_tr_b16 v[180:181], v0 offset:29696
	ds_read_b64_tr_b16 v[182:183], v0 offset:30208
	v_add_f32_e32 v2, v94, v2
	v_add_f32_e32 v2, v95, v2
	v_add_f32_e32 v2, v64, v2
	v_add_f32_e32 v2, v65, v2
	v_cvt_pk_bf16_f32 v154, v92, v93
	v_cvt_pk_bf16_f32 v155, v94, v95
	s_waitcnt lgkmcnt(12)
	v_mfma_f32_32x32x16_bf16 v[112:127], v[176:179], v[136:139], v[112:127]
	ds_read_b64_tr_b16 v[176:177], v0 offset:26624
	ds_read_b64_tr_b16 v[178:179], v0 offset:27136
	v_add_f32_e32 v2, v66, v2
	v_add_f32_e32 v2, v67, v2
	v_add_f32_e32 v2, v68, v2
	v_add_f32_e32 v6, v69, v2
	v_cvt_pk_bf16_f32 v148, v64, v65
	v_cvt_pk_bf16_f32 v149, v66, v67
	s_waitcnt lgkmcnt(12)
	v_mfma_f32_32x32x16_bf16 v[96:111], v[172:175], v[132:135], v[96:111]
	ds_read_b64_tr_b16 v[2:3], v0 offset:30720
	ds_read_b64_tr_b16 v[4:5], v0 offset:31232
	v_add_f32_e32 v6, v70, v6
	v_add_f32_e32 v6, v71, v6
	v_add_f32_e32 v6, v72, v6
	v_add_f32_e32 v14, v73, v6
	v_cvt_pk_bf16_f32 v150, v68, v69
	v_cvt_pk_bf16_f32 v151, v70, v71
	s_waitcnt lgkmcnt(12)
	v_mfma_f32_32x32x16_bf16 v[112:127], v[168:171], v[132:135], v[112:127]
	ds_read_b64_tr_b16 v[6:7], v0 offset:27648
	ds_read_b64_tr_b16 v[8:9], v0 offset:28160
	v_add_f32_e32 v14, v74, v14
	v_add_f32_e32 v14, v75, v14
	v_add_f32_e32 v14, v76, v14
	v_add_f32_e32 v14, v77, v14
	v_cvt_pk_bf16_f32 v144, v72, v73
	v_cvt_pk_bf16_f32 v145, v74, v75
	s_waitcnt lgkmcnt(11)
	v_mfma_f32_32x32x16_bf16 v[96:111], v[164:167], v[128:131], v[96:111]
	ds_read_b64_tr_b16 v[164:165], v0 offset:31744
	ds_read_b64_tr_b16 v[166:167], v0 offset:32256
	v_add_f32_e32 v0, v78, v14
	v_add_f32_e32 v0, v79, v0
	v_add_f32_e32 v0, 0, v0
	v_cvt_pk_bf16_f32 v146, v76, v77
	v_cvt_pk_bf16_f32 v147, v78, v79
	v_mfma_f32_32x32x16_bf16 v[112:127], v[160:163], v[128:131], v[112:127]
	s_add_i32 s16, s46, -2
	s_lshr_b32 s16, s16, 2
	s_and_b32 s22, s47, 0x18000
	v_mad_u64_u32 v[14:15], s[16:17], s16, v239, v[212:213]
	s_lshl_b32 s26, s22, 1
	v_lshl_add_u64 v[14:15], v[14:15], 0, s[26:27]
	s_add_i32 s16, s50, s74
	s_mov_b32 s17, m0
	s_mov_b32 m0, s16
	s_nop 0
	global_load_lds_dwordx4 v[14:15], off
	s_mov_b32 m0, s17
	s_add_i32 s16, s46, -4
	s_add_i32 s17, s47, 0xffff0000
	s_lshr_b32 s16, s16, 2
	s_and_b32 s22, s17, 0x18000
	v_mad_u64_u32 v[14:15], s[16:17], s16, v239, v[214:215]
	s_lshl_b32 s26, s22, 1
	v_lshl_add_u64 v[14:15], v[14:15], 0, s[26:27]
	s_add_i32 s16, s25, s75
	s_mov_b32 s17, m0
	s_mov_b32 m0, s16
	s_nop 0
	global_load_lds_dwordx4 v[14:15], off
	s_mov_b32 m0, s17
	v_add_f32_e32 v0, v241, v0
	s_waitcnt lgkmcnt(2)
	s_waitcnt lgkmcnt(1)
	s_waitcnt lgkmcnt(0)
	v_mov_b32_e32 v14, v112
	v_mov_b32_e32 v15, v113
	v_mov_b32_e32 v66, v114
	v_mov_b32_e32 v67, v115
	v_max3_f32 v81, v98, v99, v15
	v_max_f32_e32 v80, v96, v97
	s_waitcnt lgkmcnt(0)
	v_max3_f32 v80, v80, v14, v66
	v_max3_f32 v80, v80, v67, v100
	v_max3_f32 v81, v81, v102, v103
	s_waitcnt lgkmcnt(0)
	s_waitcnt lgkmcnt(0)
	v_max3_f32 v80, v80, v101, v116
	v_max3_f32 v81, v81, v118, v119
	v_max3_f32 v80, v80, v117, v104
	v_max3_f32 v81, v81, v106, v107
	s_waitcnt lgkmcnt(0)
	s_waitcnt lgkmcnt(0)
	v_max3_f32 v80, v80, v105, v120
	v_max3_f32 v81, v81, v122, v123
	v_max3_f32 v80, v80, v121, v108
	v_max3_f32 v81, v81, v110, v111
	v_max3_f32 v80, v80, v109, v124
	v_max3_f32 v81, v81, v126, v127
	v_max3_f32 v80, v80, v125, v81
	v_mov_b32_e32 v81, v80
	s_nop 1
	v_permlane32_swap_b32_e32 v80, v81
	v_max_f32_e32 v81, v81, v81
	v_max_f32_e32 v80, v80, v80
	v_max_f32_e32 v80, v80, v81
	v_cmp_lt_f32_e32 vcc, s36, v80
	s_cmp_lg_u64 vcc, 0
	s_cselect_b64 s[16:17], -1, 0
	s_cbranch_vccnz .LBB0_1324
.LBB0_1317:
	ds_read_b32 v230, v237 offset:256
	ds_read_b32 v231, v237 offset:384
	v_mfma_f32_32x32x16_bf16 v[32:47], v[156:159], v[192:195], v[32:47]
	v_exp_f32_e32 v80, v96
	v_exp_f32_e32 v81, v97
	v_exp_f32_e32 v82, v98
	v_exp_f32_e32 v83, v99
	v_mfma_f32_32x32x16_bf16 v[16:31], v[156:159], v[188:191], v[16:31]
	v_exp_f32_e32 v84, v100
	v_exp_f32_e32 v85, v101
	v_exp_f32_e32 v86, v102
	v_exp_f32_e32 v87, v103
	v_add_u32_e32 v96, s25, v228
	ds_read_b128 v[112:115], v96
	ds_read_b128 v[160:163], v96 offset:512
	v_mfma_f32_32x32x16_bf16 v[32:47], v[152:155], v[10:13], v[32:47]
	v_exp_f32_e32 v88, v104
	v_exp_f32_e32 v89, v105
	v_exp_f32_e32 v90, v106
	v_exp_f32_e32 v91, v107
	ds_read_b128 v[192:195], v96 offset:2048
	ds_read_b128 v[188:191], v96 offset:2560
	v_mfma_f32_32x32x16_bf16 v[16:31], v[152:155], v[180:183], v[16:31]
	v_exp_f32_e32 v92, v108
	v_exp_f32_e32 v93, v109
	v_exp_f32_e32 v94, v110
	v_exp_f32_e32 v95, v111
	ds_read_b128 v[184:187], v96 offset:4096
	ds_read_b128 v[180:183], v96 offset:4608
	v_mfma_f32_32x32x16_bf16 v[32:47], v[148:151], v[176:179], v[32:47]
	v_exp_f32_e32 v64, v14
	v_exp_f32_e32 v65, v15
	v_exp_f32_e32 v66, v66
	v_exp_f32_e32 v67, v67
	ds_read_b128 v[176:179], v96 offset:6144
	ds_read_b128 v[172:175], v96 offset:6656
	v_mfma_f32_32x32x16_bf16 v[16:31], v[148:151], v[2:5], v[16:31]
	v_exp_f32_e32 v68, v116
	v_exp_f32_e32 v69, v117
	v_exp_f32_e32 v70, v118
	v_exp_f32_e32 v71, v119
	v_mfma_f32_32x32x16_bf16 v[32:47], v[144:147], v[6:9], v[32:47]
	v_exp_f32_e32 v72, v120
	v_exp_f32_e32 v73, v121
	v_exp_f32_e32 v74, v122
	v_exp_f32_e32 v75, v123
	v_mfma_f32_32x32x16_bf16 v[16:31], v[144:147], v[164:167], v[16:31]
	v_exp_f32_e32 v76, v124
	v_exp_f32_e32 v77, v125
	v_exp_f32_e32 v78, v126
	v_exp_f32_e32 v79, v127
	s_waitcnt vmcnt(2) lgkmcnt(0)
	s_barrier
	s_andn2_b64 vcc, exec, s[16:17]
	s_cbranch_vccnz .LBB0_1319
	s_waitcnt lgkmcnt(0)
	ds_read_b128 v[2:5], v224 offset:49248
	ds_read_b128 v[6:9], v224 offset:49216
	ds_read_b128 v[10:13], v224 offset:49184
	ds_read_b128 v[96:99], v224 offset:49152
	s_waitcnt lgkmcnt(3)
	v_mul_f32_e32 v46, v46, v4
	v_mul_f32_e32 v47, v47, v5
	s_waitcnt lgkmcnt(2)
	v_mul_f32_e32 v42, v42, v8
	v_mul_f32_e32 v43, v43, v9
	s_waitcnt lgkmcnt(1)
	v_mul_f32_e32 v38, v38, v12
	v_mul_f32_e32 v39, v39, v13
	s_waitcnt lgkmcnt(0)
	v_mul_f32_e32 v34, v34, v98
	v_mul_f32_e32 v35, v35, v99
	v_mul_f32_e32 v44, v44, v2
	v_mul_f32_e32 v45, v45, v3
	v_mul_f32_e32 v40, v40, v6
	v_mul_f32_e32 v41, v41, v7
	v_mul_f32_e32 v36, v36, v10
	v_mul_f32_e32 v37, v37, v11
	v_mul_f32_e32 v32, v32, v96
	v_mul_f32_e32 v33, v33, v97
	v_mul_f32_e32 v30, v30, v4
	v_mul_f32_e32 v31, v31, v5
	v_mul_f32_e32 v26, v26, v8
	v_mul_f32_e32 v27, v27, v9
	v_mul_f32_e32 v22, v22, v12
	v_mul_f32_e32 v23, v23, v13
	v_mul_f32_e32 v18, v18, v98
	v_mul_f32_e32 v19, v19, v99
	v_mul_f32_e32 v28, v28, v2
	v_mul_f32_e32 v29, v29, v3
	v_mul_f32_e32 v24, v24, v6
	v_mul_f32_e32 v25, v25, v7
	v_mul_f32_e32 v20, v20, v10
	v_mul_f32_e32 v21, v21, v11
	v_mul_f32_e32 v16, v16, v96
	v_mul_f32_e32 v17, v17, v97
.LBB0_1319:
	s_waitcnt lgkmcnt(8)
	v_mfma_f32_32x32x2_f32 v[96:111], v230, v236, v[48:63]
	s_add_i32 s16, s25, 0x2000
	s_cmpk_lg_i32 s25, 0x4000
	s_cselect_b32 s78, s16, 0
	v_add_u32_e32 v14, s50, v240
	ds_read_b64_tr_b16 v[168:169], v14 offset:24576
	ds_read_b64_tr_b16 v[170:171], v14 offset:25088
	v_add_f32_e32 v2, v80, v81
	v_add_f32_e32 v2, v82, v2
	v_add_f32_e32 v2, v83, v2
	v_add_f32_e32 v2, v84, v2
	v_add_f32_e32 v2, v85, v2
	v_cvt_pk_bf16_f32 v156, v80, v81
	v_cvt_pk_bf16_f32 v157, v82, v83
	s_waitcnt lgkmcnt(9)
	v_mfma_f32_32x32x16_bf16 v[96:111], v[112:115], v[140:143], v[96:111]
	ds_read_b64_tr_b16 v[164:165], v14 offset:28672
	ds_read_b64_tr_b16 v[166:167], v14 offset:29184
	v_add_f32_e32 v2, v86, v2
	v_add_f32_e32 v2, v87, v2
	v_add_f32_e32 v2, v88, v2
	v_add_f32_e32 v2, v89, v2
	v_cvt_pk_bf16_f32 v158, v84, v85
	v_cvt_pk_bf16_f32 v159, v86, v87
	s_waitcnt lgkmcnt(10)
	v_mfma_f32_32x32x2_f32 v[112:127], v231, v236, v[48:63]
	v_mfma_f32_32x32x16_bf16 v[112:127], v[160:163], v[140:143], v[112:127]
	ds_read_b64_tr_b16 v[10:11], v14 offset:25600
	ds_read_b64_tr_b16 v[12:13], v14 offset:26112
	v_add_f32_e32 v2, v90, v2
	v_add_f32_e32 v2, v91, v2
	v_add_f32_e32 v2, v92, v2
	v_add_f32_e32 v2, v93, v2
	v_cvt_pk_bf16_f32 v152, v88, v89
	v_cvt_pk_bf16_f32 v153, v90, v91
	s_waitcnt lgkmcnt(11)
	v_mfma_f32_32x32x16_bf16 v[96:111], v[192:195], v[136:139], v[96:111]
	ds_read_b64_tr_b16 v[160:161], v14 offset:29696
	ds_read_b64_tr_b16 v[162:163], v14 offset:30208
	v_add_f32_e32 v2, v94, v2
	v_add_f32_e32 v2, v95, v2
	v_add_f32_e32 v2, v64, v2
	v_add_f32_e32 v2, v65, v2
	v_cvt_pk_bf16_f32 v154, v92, v93
	v_cvt_pk_bf16_f32 v155, v94, v95
	s_waitcnt lgkmcnt(12)
	v_mfma_f32_32x32x16_bf16 v[112:127], v[188:191], v[136:139], v[112:127]
	ds_read_b64_tr_b16 v[196:197], v14 offset:26624
	ds_read_b64_tr_b16 v[198:199], v14 offset:27136
	v_add_f32_e32 v2, v66, v2
	v_add_f32_e32 v2, v67, v2
	v_add_f32_e32 v2, v68, v2
	v_add_f32_e32 v6, v69, v2
	v_cvt_pk_bf16_f32 v148, v64, v65
	v_cvt_pk_bf16_f32 v149, v66, v67
	s_waitcnt lgkmcnt(12)
	v_mfma_f32_32x32x16_bf16 v[96:111], v[184:187], v[132:135], v[96:111]
	ds_read_b64_tr_b16 v[2:3], v14 offset:30720
	ds_read_b64_tr_b16 v[4:5], v14 offset:31232
	v_add_f32_e32 v6, v70, v6
	v_add_f32_e32 v6, v71, v6
	v_add_f32_e32 v6, v72, v6
	v_add_f32_e32 v15, v73, v6
	v_cvt_pk_bf16_f32 v150, v68, v69
	v_cvt_pk_bf16_f32 v151, v70, v71
	s_waitcnt lgkmcnt(12)
	v_mfma_f32_32x32x16_bf16 v[112:127], v[180:183], v[132:135], v[112:127]
	ds_read_b64_tr_b16 v[6:7], v14 offset:27648
	ds_read_b64_tr_b16 v[8:9], v14 offset:28160
	v_add_f32_e32 v15, v74, v15
	v_add_f32_e32 v15, v75, v15
	v_add_f32_e32 v15, v76, v15
	v_add_f32_e32 v15, v77, v15
	v_cvt_pk_bf16_f32 v144, v72, v73
	v_cvt_pk_bf16_f32 v145, v74, v75
	s_waitcnt lgkmcnt(11)
	v_mfma_f32_32x32x16_bf16 v[96:111], v[176:179], v[128:131], v[96:111]
	ds_read_b64_tr_b16 v[192:193], v14 offset:31744
	ds_read_b64_tr_b16 v[194:195], v14 offset:32256
	v_add_f32_e32 v14, v78, v15
	v_add_f32_e32 v14, v79, v14
	v_add_f32_e32 v80, 0, v14
	v_cvt_pk_bf16_f32 v146, v76, v77
	v_cvt_pk_bf16_f32 v147, v78, v79
	v_mfma_f32_32x32x16_bf16 v[112:127], v[172:175], v[128:131], v[112:127]
	s_add_i32 s16, s46, -1
	s_add_i32 s17, s47, 0xfffe8000
	s_lshr_b32 s16, s16, 2
	s_and_b32 s22, s17, 0x18000
	v_mad_u64_u32 v[14:15], s[16:17], s16, v239, v[212:213]
	s_lshl_b32 s26, s22, 1
	v_lshl_add_u64 v[14:15], v[14:15], 0, s[26:27]
	s_add_i32 s16, s25, s74
	s_mov_b32 s17, m0
	s_mov_b32 m0, s16
	s_nop 0
	global_load_lds_dwordx4 v[14:15], off
	s_mov_b32 m0, s17
	s_add_i32 s50, s46, -3
	s_add_i32 s17, s47, 0xffff8000
	s_lshr_b32 s16, s50, 2
	s_and_b32 s22, s17, 0x18000
	v_mad_u64_u32 v[14:15], s[16:17], s16, v239, v[214:215]
	s_lshl_b32 s26, s22, 1
	v_lshl_add_u64 v[14:15], v[14:15], 0, s[26:27]
	s_add_i32 s16, s78, s75
	s_mov_b32 s17, m0
	s_mov_b32 m0, s16
	s_nop 0
	global_load_lds_dwordx4 v[14:15], off
	s_mov_b32 m0, s17
	v_add_f32_e32 v241, v0, v80
	s_waitcnt lgkmcnt(2)
	s_waitcnt lgkmcnt(1)
	s_waitcnt lgkmcnt(0)
	v_mov_b32_e32 v64, v96
	s_waitcnt lgkmcnt(0)
	v_max_f32_e32 v81, v64, v97
	v_max3_f32 v81, v81, v112, v114
	v_max3_f32 v81, v81, v115, v100
	s_waitcnt lgkmcnt(0)
	s_waitcnt lgkmcnt(0)
	v_max3_f32 v81, v81, v101, v116
	v_max3_f32 v81, v81, v117, v104
	v_max3_f32 v81, v81, v105, v120
	s_waitcnt lgkmcnt(0)
	s_waitcnt lgkmcnt(0)
	v_max3_f32 v96, v98, v99, v113
	v_max3_f32 v96, v96, v102, v103
	v_max3_f32 v96, v96, v118, v119
	v_max3_f32 v96, v96, v106, v107
	v_max3_f32 v96, v96, v122, v123
	v_max3_f32 v81, v81, v121, v108
	v_max3_f32 v96, v96, v110, v111
	v_max3_f32 v81, v81, v109, v124
	v_max3_f32 v96, v96, v126, v127
	v_max3_f32 v0, v81, v125, v96
	v_mov_b32_e32 v80, v0
	s_nop 1
	v_permlane32_swap_b32_e32 v0, v80
	v_max_f32_e32 v80, v80, v80
	v_max_f32_e32 v0, v0, v0
	v_max_f32_e32 v0, v0, v80
	v_cmp_lt_f32_e32 vcc, s36, v0
	s_cmp_lg_u64 vcc, 0
	s_cselect_b64 s[16:17], -1, 0
	s_cbranch_vccnz .LBB0_1327
.LBB0_1320:
	ds_read_b32 v230, v237 offset:512
	ds_read_b32 v231, v237 offset:640
	v_mfma_f32_32x32x16_bf16 v[32:47], v[156:159], v[168:171], v[32:47]
	v_exp_f32_e32 v80, v64
	v_exp_f32_e32 v81, v97
	v_exp_f32_e32 v82, v98
	v_exp_f32_e32 v83, v99
	v_mfma_f32_32x32x16_bf16 v[16:31], v[156:159], v[164:167], v[16:31]
	v_exp_f32_e32 v84, v100
	v_exp_f32_e32 v85, v101
	v_exp_f32_e32 v86, v102
	v_exp_f32_e32 v87, v103
	v_add_u32_e32 v0, s78, v228
	ds_read_b128 v[188:191], v0
	ds_read_b128 v[184:187], v0 offset:512
	v_mfma_f32_32x32x16_bf16 v[32:47], v[152:155], v[10:13], v[32:47]
	v_exp_f32_e32 v88, v104
	v_exp_f32_e32 v89, v105
	v_exp_f32_e32 v90, v106
	v_exp_f32_e32 v91, v107
	ds_read_b128 v[180:183], v0 offset:2048
	ds_read_b128 v[176:179], v0 offset:2560
	v_mfma_f32_32x32x16_bf16 v[16:31], v[152:155], v[160:163], v[16:31]
	v_exp_f32_e32 v92, v108
	v_exp_f32_e32 v93, v109
	v_exp_f32_e32 v94, v110
	v_exp_f32_e32 v95, v111
	ds_read_b128 v[172:175], v0 offset:4096
	ds_read_b128 v[168:171], v0 offset:4608
	v_mfma_f32_32x32x16_bf16 v[32:47], v[148:151], v[196:199], v[32:47]
	v_exp_f32_e32 v64, v112
	v_exp_f32_e32 v65, v113
	v_exp_f32_e32 v66, v114
	v_exp_f32_e32 v67, v115
	ds_read_b128 v[164:167], v0 offset:6144
	ds_read_b128 v[160:163], v0 offset:6656
	v_mfma_f32_32x32x16_bf16 v[16:31], v[148:151], v[2:5], v[16:31]
	v_exp_f32_e32 v68, v116
	v_exp_f32_e32 v69, v117
	v_exp_f32_e32 v70, v118
	v_exp_f32_e32 v71, v119
	v_mfma_f32_32x32x16_bf16 v[32:47], v[144:147], v[6:9], v[32:47]
	v_exp_f32_e32 v72, v120
	v_exp_f32_e32 v73, v121
	v_exp_f32_e32 v74, v122
	v_exp_f32_e32 v75, v123
	v_mfma_f32_32x32x16_bf16 v[16:31], v[144:147], v[192:195], v[16:31]
	v_exp_f32_e32 v76, v124
	v_exp_f32_e32 v77, v125
	v_exp_f32_e32 v78, v126
	v_exp_f32_e32 v79, v127
	s_waitcnt vmcnt(2) lgkmcnt(0)
	s_barrier
	s_andn2_b64 vcc, exec, s[16:17]
	s_cbranch_vccnz .LBB0_1322
	s_waitcnt lgkmcnt(0)
	ds_read_b128 v[2:5], v224 offset:49248
	ds_read_b128 v[6:9], v224 offset:49216
	ds_read_b128 v[10:13], v224 offset:49184
	ds_read_b128 v[96:99], v224 offset:49152
	s_waitcnt lgkmcnt(3)
	v_mul_f32_e32 v46, v46, v4
	v_mul_f32_e32 v47, v47, v5
	s_waitcnt lgkmcnt(2)
	v_mul_f32_e32 v42, v42, v8
	v_mul_f32_e32 v43, v43, v9
	s_waitcnt lgkmcnt(1)
	v_mul_f32_e32 v38, v38, v12
	v_mul_f32_e32 v39, v39, v13
	s_waitcnt lgkmcnt(0)
	v_mul_f32_e32 v34, v34, v98
	v_mul_f32_e32 v35, v35, v99
	v_mul_f32_e32 v44, v44, v2
	v_mul_f32_e32 v45, v45, v3
	v_mul_f32_e32 v40, v40, v6
	v_mul_f32_e32 v41, v41, v7
	v_mul_f32_e32 v36, v36, v10
	v_mul_f32_e32 v37, v37, v11
	v_mul_f32_e32 v32, v32, v96
	v_mul_f32_e32 v33, v33, v97
	v_mul_f32_e32 v30, v30, v4
	v_mul_f32_e32 v31, v31, v5
	v_mul_f32_e32 v26, v26, v8
	v_mul_f32_e32 v27, v27, v9
	v_mul_f32_e32 v22, v22, v12
	v_mul_f32_e32 v23, v23, v13
	v_mul_f32_e32 v18, v18, v98
	v_mul_f32_e32 v19, v19, v99
	v_mul_f32_e32 v28, v28, v2
	v_mul_f32_e32 v29, v29, v3
	v_mul_f32_e32 v24, v24, v6
	v_mul_f32_e32 v25, v25, v7
	v_mul_f32_e32 v20, v20, v10
	v_mul_f32_e32 v21, v21, v11
	v_mul_f32_e32 v16, v16, v96
	v_mul_f32_e32 v17, v17, v97
.LBB0_1322:
	s_add_i32 s16, s78, 0x2000
	s_cmpk_lg_i32 s78, 0x4000
	s_cselect_b32 s64, s16, 0
	s_add_i32 s46, s46, 2
	s_add_i32 s47, s47, 0x10000
	s_cmp_ge_u32 s46, s77
	v_add_u32_e32 v200, 0x200, v200
	v_add_u32_e32 v237, 0x200, v237
	s_cbranch_scc1 .LBB0_1331
	s_mov_b32 s16, s25
	s_mov_b32 s50, s78
	s_mov_b32 s25, s64
	s_branch .LBB0_1316
.LBB0_1324:
	v_max_f32_e32 v48, v80, v80
	v_max_f32_e32 v80, 0, v48
	v_exp_f32_e64 v81, -v80
	v_add_f32_e32 v229, v229, v80
	v_xor_b32_e32 v48, 0x80000000, v229
	v_mov_b32_e32 v49, v48
	v_mov_b32_e32 v50, v48
	v_mov_b32_e32 v51, v48
	v_mov_b32_e32 v52, v48
	v_mov_b32_e32 v53, v48
	v_mov_b32_e32 v54, v48
	v_mov_b32_e32 v55, v48
	v_mov_b32_e32 v56, v48
	v_mov_b32_e32 v57, v48
	v_mov_b32_e32 v58, v48
	v_mov_b32_e32 v59, v48
	v_mov_b32_e32 v60, v48
	v_mov_b32_e32 v61, v48
	v_mov_b32_e32 v62, v48
	v_mov_b32_e32 v63, v48
	s_and_saveexec_b64 s[22:23], s[2:3]
	ds_write_b32 v226, v81 offset:49152
	s_or_b64 exec, exec, s[22:23]
	v_sub_f32_e32 v96, v96, v80
	v_sub_f32_e32 v97, v97, v80
	v_sub_f32_e32 v98, v98, v80
	v_sub_f32_e32 v99, v99, v80
	v_sub_f32_e32 v100, v100, v80
	v_sub_f32_e32 v101, v101, v80
	v_sub_f32_e32 v102, v102, v80
	v_sub_f32_e32 v103, v103, v80
	v_sub_f32_e32 v104, v104, v80
	v_sub_f32_e32 v105, v105, v80
	v_sub_f32_e32 v106, v106, v80
	v_sub_f32_e32 v107, v107, v80
	v_sub_f32_e32 v108, v108, v80
	v_sub_f32_e32 v109, v109, v80
	v_sub_f32_e32 v110, v110, v80
	v_sub_f32_e32 v111, v111, v80
	v_sub_f32_e32 v14, v14, v80
	v_sub_f32_e32 v15, v15, v80
	v_sub_f32_e32 v66, v66, v80
	v_sub_f32_e32 v67, v67, v80
	v_sub_f32_e32 v116, v116, v80
	v_sub_f32_e32 v117, v117, v80
	v_sub_f32_e32 v118, v118, v80
	v_sub_f32_e32 v119, v119, v80
	v_sub_f32_e32 v120, v120, v80
	v_sub_f32_e32 v121, v121, v80
	v_sub_f32_e32 v122, v122, v80
	v_sub_f32_e32 v123, v123, v80
	v_sub_f32_e32 v124, v124, v80
	v_sub_f32_e32 v125, v125, v80
	v_sub_f32_e32 v126, v126, v80
	v_sub_f32_e32 v127, v127, v80
	v_mul_f32_e32 v0, v0, v81
	s_branch .LBB0_1317
.LBB0_1327:
	v_max_f32_e32 v0, v0, v0
	v_max_f32_e32 v0, 0, v0
	v_exp_f32_e64 v80, -v0
	v_add_f32_e32 v229, v229, v0
	v_xor_b32_e32 v48, 0x80000000, v229
	v_mov_b32_e32 v49, v48
	v_mov_b32_e32 v50, v48
	v_mov_b32_e32 v51, v48
	v_mov_b32_e32 v52, v48
	v_mov_b32_e32 v53, v48
	v_mov_b32_e32 v54, v48
	v_mov_b32_e32 v55, v48
	v_mov_b32_e32 v56, v48
	v_mov_b32_e32 v57, v48
	v_mov_b32_e32 v58, v48
	v_mov_b32_e32 v59, v48
	v_mov_b32_e32 v60, v48
	v_mov_b32_e32 v61, v48
	v_mov_b32_e32 v62, v48
	v_mov_b32_e32 v63, v48
	s_and_saveexec_b64 s[22:23], s[2:3]
	ds_write_b32 v226, v80 offset:49152
	s_or_b64 exec, exec, s[22:23]
	v_sub_f32_e32 v64, v64, v0
	v_sub_f32_e32 v97, v97, v0
	v_sub_f32_e32 v98, v98, v0
	v_sub_f32_e32 v99, v99, v0
	v_sub_f32_e32 v100, v100, v0
	v_sub_f32_e32 v101, v101, v0
	v_sub_f32_e32 v102, v102, v0
	v_sub_f32_e32 v103, v103, v0
	v_sub_f32_e32 v104, v104, v0
	v_sub_f32_e32 v105, v105, v0
	v_sub_f32_e32 v106, v106, v0
	v_sub_f32_e32 v107, v107, v0
	v_sub_f32_e32 v108, v108, v0
	v_sub_f32_e32 v109, v109, v0
	v_sub_f32_e32 v110, v110, v0
	v_sub_f32_e32 v111, v111, v0
	v_sub_f32_e32 v112, v112, v0
	v_sub_f32_e32 v113, v113, v0
	v_sub_f32_e32 v114, v114, v0
	v_sub_f32_e32 v115, v115, v0
	v_sub_f32_e32 v116, v116, v0
	v_sub_f32_e32 v117, v117, v0
	v_sub_f32_e32 v118, v118, v0
	v_sub_f32_e32 v119, v119, v0
	v_sub_f32_e32 v120, v120, v0
	v_sub_f32_e32 v121, v121, v0
	v_sub_f32_e32 v122, v122, v0
	v_sub_f32_e32 v123, v123, v0
	v_sub_f32_e32 v124, v124, v0
	v_sub_f32_e32 v125, v125, v0
	v_sub_f32_e32 v126, v126, v0
	v_sub_f32_e32 v127, v127, v0
	v_mul_f32_e32 v241, v241, v80
	s_branch .LBB0_1320

.LBB0_1331:
	s_waitcnt lgkmcnt(0)
	v_mov_b32_e32 v230, 1
	v_mov_b32_e32 v231, 0x358637bd
	v_mov_b32_e32 v236, 0x6101000
	v_mov_b32_e32 v237, 0x6100000
	s_xor_b64 s[16:17], s[4:5], -1
	s_add_i32 s2, s50, 1
	s_cmp_ge_u32 s2, s77
	s_cbranch_scc1 .LBB0_1381
	s_lshl_b32 s4, s50, 6
	s_addk_i32 s4, 0x7b
	v_add_u32_e32 v0, s4, v221
	s_lshl_b32 s4, s24, 2
	s_sub_i32 s65, 0, s4
	s_lshl_b32 s4, s50, 8
	s_add_i32 s4, s4, 0
	s_add_i32 s4, s4, 0x14800
	v_cmp_gt_u32_e64 s[2:3], 32, v217
	v_subrev_u32_e32 v0, s71, v0
	s_add_i32 s58, s50, 2
	v_lshl_add_u32 v14, v219, 4, s4
	s_lshl_b32 s79, s50, 15
	.p2align	6
